# o30 + last 4 K-blocks (704 blocks) of the FFN2 gate/up fold conversion moved from WIN's idle round to the GU1 idle tail
# baseline (speedup 1.0000x reference)
.Lw1d_loop:
	v_readfirstlane_b32 s98, v18
	s_nop 3
	s_cmpk_ge_u32 s98, 0x8e0
	s_cbranch_scc1 .Lw1d_rest
	s_cmpk_ge_u32 s98, 0x780
	s_cbranch_scc1 .Lw2t_item
	s_cmpk_ge_u32 s98, 0x580
	s_cbranch_scc1 .Lwo_item
	s_lshr_b32 s99, s98, 4
	s_and_b32 s100, s98, 15
	s_lshl_b32 s101, s99, 19
	s_lshl_b32 s0, s100, 9
	s_add_u32 s0, s0, s101
	s_add_u32 s0, s8, s0
	s_addc_u32 s1, s9, 0
	s_mul_i32 s2, s100, 0x160000
	s_lshl_b32 s3, s99, 7
	s_add_u32 s2, s2, s3
	s_add_u32 s2, s2, 0x2d60200
	s_add_u32 s2, s86, s2
	s_addc_u32 s3, s87, 0
	s_add_u32 s4, s2, 0xb0000
	s_addc_u32 s5, s3, 0
	global_load_dwordx4 v[154:157], v8, s[0:1] nt
	global_load_dwordx4 v[204:207], v8, s[0:1] offset:256 nt
	s_add_u32 s0, s0, 0x2000
	s_addc_u32 s1, s1, 0
	global_load_dwordx4 v[158:161], v8, s[0:1] nt
	global_load_dwordx4 v[208:211], v8, s[0:1] offset:256 nt
	s_add_u32 s0, s0, 0x2000
	s_addc_u32 s1, s1, 0
	global_load_dwordx4 v[162:165], v8, s[0:1] nt
	global_load_dwordx4 v[212:215], v8, s[0:1] offset:256 nt
	s_add_u32 s0, s0, 0x2000
	s_addc_u32 s1, s1, 0
	global_load_dwordx4 v[166:169], v8, s[0:1] nt
	global_load_dwordx4 v[216:219], v8, s[0:1] offset:256 nt
	s_add_u32 s0, s0, 0x2000
	s_addc_u32 s1, s1, 0
	global_load_dwordx4 v[170:173], v8, s[0:1] nt
	global_load_dwordx4 v[220:223], v8, s[0:1] offset:256 nt
	s_add_u32 s0, s0, 0x2000
	s_addc_u32 s1, s1, 0
	global_load_dwordx4 v[174:177], v8, s[0:1] nt
	global_load_dwordx4 v[224:227], v8, s[0:1] offset:256 nt
	s_add_u32 s0, s0, 0x2000
	s_addc_u32 s1, s1, 0
	global_load_dwordx4 v[178:181], v8, s[0:1] nt
	global_load_dwordx4 v[228:231], v8, s[0:1] offset:256 nt
	s_add_u32 s0, s0, 0x2000
	s_addc_u32 s1, s1, 0
	global_load_dwordx4 v[182:185], v8, s[0:1] nt
	global_load_dwordx4 v[232:235], v8, s[0:1] offset:256 nt
	s_add_u32 s0, s0, 0x2000
	s_addc_u32 s1, s1, 0
	global_load_dwordx4 v[186:189], v8, s[0:1] nt
	global_load_dwordx4 v[236:239], v8, s[0:1] offset:256 nt
	s_add_u32 s0, s0, 0x2000
	s_addc_u32 s1, s1, 0
	global_load_dwordx4 v[190:193], v8, s[0:1] nt
	global_load_dwordx4 v[240:243], v8, s[0:1] offset:256 nt
	s_add_u32 s0, s0, 0x2000
	s_addc_u32 s1, s1, 0
	global_load_dwordx4 v[194:197], v8, s[0:1] nt
	global_load_dwordx4 v[244:247], v8, s[0:1] offset:256 nt
	s_add_u32 s0, s0, 0x2000
	s_addc_u32 s1, s1, 0
	global_load_dwordx4 v[198:201], v8, s[0:1] nt
	global_load_dwordx4 v[248:251], v8, s[0:1] offset:256 nt
	s_add_u32 s0, s0, 0x2000
	s_addc_u32 s1, s1, 0
	global_load_dwordx4 v[130:133], v8, s[0:1] nt
	global_load_dwordx4 v[50:53], v8, s[0:1] offset:256 nt
	s_add_u32 s0, s0, 0x2000
	s_addc_u32 s1, s1, 0
	global_load_dwordx4 v[134:137], v8, s[0:1] nt
	global_load_dwordx4 v[54:57], v8, s[0:1] offset:256 nt
	s_add_u32 s0, s0, 0x2000
	s_addc_u32 s1, s1, 0
	global_load_dwordx4 v[138:141], v8, s[0:1] nt
	global_load_dwordx4 v[58:61], v8, s[0:1] offset:256 nt
	s_add_u32 s0, s0, 0x2000
	s_addc_u32 s1, s1, 0
	global_load_dwordx4 v[142:145], v8, s[0:1] nt
	global_load_dwordx4 v[62:65], v8, s[0:1] offset:256 nt
	s_mov_b64 exec, 1
	global_atomic_add v18, v16, v17, s[6:7] sc0
	s_mov_b64 exec, -1
	s_waitcnt vmcnt(1)
	v_cvt_pk_bf16_f32 v20, v154, v158
	v_cvt_pk_bf16_f32 v21, v162, v166
	v_cvt_pk_bf16_f32 v22, v170, v174
	v_cvt_pk_bf16_f32 v23, v178, v182
	global_store_dwordx4 v12, v[20:23], s[2:3]
	v_cvt_pk_bf16_f32 v24, v186, v190
	v_cvt_pk_bf16_f32 v25, v194, v198
	v_cvt_pk_bf16_f32 v26, v130, v134
	v_cvt_pk_bf16_f32 v27, v138, v142
	global_store_dwordx4 v12, v[24:27], s[2:3] offset:16
	v_cvt_pk_bf16_f32 v28, v155, v159
	v_cvt_pk_bf16_f32 v29, v163, v167
	v_cvt_pk_bf16_f32 v30, v171, v175
	v_cvt_pk_bf16_f32 v31, v179, v183
	global_store_dwordx4 v13, v[28:31], s[2:3]
	v_cvt_pk_bf16_f32 v32, v187, v191
	v_cvt_pk_bf16_f32 v33, v195, v199
	v_cvt_pk_bf16_f32 v34, v131, v135
	v_cvt_pk_bf16_f32 v35, v139, v143
	global_store_dwordx4 v13, v[32:35], s[2:3] offset:16
	v_cvt_pk_bf16_f32 v36, v156, v160
	v_cvt_pk_bf16_f32 v37, v164, v168
	v_cvt_pk_bf16_f32 v38, v172, v176
	v_cvt_pk_bf16_f32 v39, v180, v184
	global_store_dwordx4 v14, v[36:39], s[2:3]
	v_cvt_pk_bf16_f32 v40, v188, v192
	v_cvt_pk_bf16_f32 v41, v196, v200
	v_cvt_pk_bf16_f32 v42, v132, v136
	v_cvt_pk_bf16_f32 v43, v140, v144
	global_store_dwordx4 v14, v[40:43], s[2:3] offset:16
	v_cvt_pk_bf16_f32 v20, v157, v161
	v_cvt_pk_bf16_f32 v21, v165, v169
	v_cvt_pk_bf16_f32 v22, v173, v177
	v_cvt_pk_bf16_f32 v23, v181, v185
	global_store_dwordx4 v15, v[20:23], s[2:3]
	v_cvt_pk_bf16_f32 v24, v189, v193
	v_cvt_pk_bf16_f32 v25, v197, v201
	v_cvt_pk_bf16_f32 v26, v133, v137
	v_cvt_pk_bf16_f32 v27, v141, v145
	global_store_dwordx4 v15, v[24:27], s[2:3] offset:16
	v_cvt_pk_bf16_f32 v28, v204, v208
	v_cvt_pk_bf16_f32 v29, v212, v216
	v_cvt_pk_bf16_f32 v30, v220, v224
	v_cvt_pk_bf16_f32 v31, v228, v232
	global_store_dwordx4 v12, v[28:31], s[4:5]
	v_cvt_pk_bf16_f32 v32, v236, v240
	v_cvt_pk_bf16_f32 v33, v244, v248
	v_cvt_pk_bf16_f32 v34, v50, v54
	v_cvt_pk_bf16_f32 v35, v58, v62
	global_store_dwordx4 v12, v[32:35], s[4:5] offset:16
	v_cvt_pk_bf16_f32 v36, v205, v209
	v_cvt_pk_bf16_f32 v37, v213, v217
	v_cvt_pk_bf16_f32 v38, v221, v225
	v_cvt_pk_bf16_f32 v39, v229, v233
	global_store_dwordx4 v13, v[36:39], s[4:5]
	v_cvt_pk_bf16_f32 v40, v237, v241
	v_cvt_pk_bf16_f32 v41, v245, v249
	v_cvt_pk_bf16_f32 v42, v51, v55
	v_cvt_pk_bf16_f32 v43, v59, v63
	global_store_dwordx4 v13, v[40:43], s[4:5] offset:16
	v_cvt_pk_bf16_f32 v20, v206, v210
	v_cvt_pk_bf16_f32 v21, v214, v218
	v_cvt_pk_bf16_f32 v22, v222, v226
	v_cvt_pk_bf16_f32 v23, v230, v234
	global_store_dwordx4 v14, v[20:23], s[4:5]
	v_cvt_pk_bf16_f32 v24, v238, v242
	v_cvt_pk_bf16_f32 v25, v246, v250
	v_cvt_pk_bf16_f32 v26, v52, v56
	v_cvt_pk_bf16_f32 v27, v60, v64
	global_store_dwordx4 v14, v[24:27], s[4:5] offset:16
	v_cvt_pk_bf16_f32 v28, v207, v211
	v_cvt_pk_bf16_f32 v29, v215, v219
	v_cvt_pk_bf16_f32 v30, v223, v227
	v_cvt_pk_bf16_f32 v31, v231, v235
	global_store_dwordx4 v15, v[28:31], s[4:5]
	v_cvt_pk_bf16_f32 v32, v239, v243
	v_cvt_pk_bf16_f32 v33, v247, v251
	v_cvt_pk_bf16_f32 v34, v53, v57
	v_cvt_pk_bf16_f32 v35, v61, v65
	global_store_dwordx4 v15, v[32:35], s[4:5] offset:16
	s_waitcnt vmcnt(16)
	s_branch .Lw1d_loop

.Lw2t_item:
	s_sub_u32 s98, s98, 0x780
	s_lshl_b32 s99, s98, 1
	s_add_u32 s99, s99, 0x1340
	s_mul_i32 s100, s99, 0xba2f
	s_lshr_b32 s100, s100, 23
	s_mul_i32 s101, s100, 0xb0
	s_sub_u32 s101, s99, s101
	s_and_b32 s70, s101, 2
	s_cmp_eq_u32 s70, 0
	s_cselect_b32 s72, s60, s62
	s_cselect_b32 s73, s61, s63
	s_lshr_b32 s70, s101, 2
	s_lshl_b32 s70, s70, 9
	s_mul_i32 s71, s100, 0x160000
	s_add_u32 s70, s70, s71
	s_add_u32 s0, s72, s70
	s_addc_u32 s1, s73, 0
	s_lshl_b32 s70, s101, 18
	s_lshl_b32 s71, s100, 7
	s_add_u32 s70, s70, s71
	s_add_u32 s2, s68, s70
	s_addc_u32 s3, s69, 0
	s_add_u32 s4, s2, 0x40000
	s_addc_u32 s5, s3, 0
	s_lshl_b32 s70, s101, 8
	s_add_u32 s72, s64, s70
	s_addc_u32 s73, s65, 0
	s_add_u32 s74, s66, s70
	s_addc_u32 s75, s67, 0
	s_add_u32 s76, s72, 0x100
	s_addc_u32 s77, s73, 0
	s_add_u32 s78, s74, 0x100
	s_addc_u32 s79, s75, 0
	s_lshl_b32 s70, s100, 8
	s_add_u32 s32, s56, s70
	s_addc_u32 s33, s57, 0
	s_add_u32 s34, s58, s70
	s_addc_u32 s35, s59, 0
	global_load_dwordx4 v[66:69], v126, s[32:33] offset:0
	global_load_dwordx4 v[82:85], v126, s[34:35] offset:0
	global_load_dwordx4 v[70:73], v126, s[32:33] offset:16
	global_load_dwordx4 v[86:89], v126, s[34:35] offset:16
	global_load_dwordx4 v[74:77], v126, s[32:33] offset:32
	global_load_dwordx4 v[90:93], v126, s[34:35] offset:32
	global_load_dwordx4 v[78:81], v126, s[32:33] offset:48
	global_load_dwordx4 v[94:97], v126, s[34:35] offset:48
	global_load_dwordx4 v[154:157], v124, s[0:1] nt
	global_load_dwordx4 v[204:207], v124, s[0:1] offset:256 nt
	s_add_u32 s0, s0, 0x5800
	s_addc_u32 s1, s1, 0
	global_load_dwordx4 v[158:161], v124, s[0:1] nt
	global_load_dwordx4 v[208:211], v124, s[0:1] offset:256 nt
	s_add_u32 s0, s0, 0x5800
	s_addc_u32 s1, s1, 0
	global_load_dwordx4 v[162:165], v124, s[0:1] nt
	global_load_dwordx4 v[212:215], v124, s[0:1] offset:256 nt
	s_add_u32 s0, s0, 0x5800
	s_addc_u32 s1, s1, 0
	global_load_dwordx4 v[166:169], v124, s[0:1] nt
	global_load_dwordx4 v[216:219], v124, s[0:1] offset:256 nt
	s_add_u32 s0, s0, 0x5800
	s_addc_u32 s1, s1, 0
	global_load_dwordx4 v[170:173], v124, s[0:1] nt
	global_load_dwordx4 v[220:223], v124, s[0:1] offset:256 nt
	s_add_u32 s0, s0, 0x5800
	s_addc_u32 s1, s1, 0
	global_load_dwordx4 v[174:177], v124, s[0:1] nt
	global_load_dwordx4 v[224:227], v124, s[0:1] offset:256 nt
	s_add_u32 s0, s0, 0x5800
	s_addc_u32 s1, s1, 0
	global_load_dwordx4 v[178:181], v124, s[0:1] nt
	global_load_dwordx4 v[228:231], v124, s[0:1] offset:256 nt
	s_add_u32 s0, s0, 0x5800
	s_addc_u32 s1, s1, 0
	global_load_dwordx4 v[182:185], v124, s[0:1] nt
	global_load_dwordx4 v[232:235], v124, s[0:1] offset:256 nt
	s_add_u32 s0, s0, 0x5800
	s_addc_u32 s1, s1, 0
	global_load_dwordx4 v[186:189], v124, s[0:1] nt
	global_load_dwordx4 v[236:239], v124, s[0:1] offset:256 nt
	s_add_u32 s0, s0, 0x5800
	s_addc_u32 s1, s1, 0
	global_load_dwordx4 v[190:193], v124, s[0:1] nt
	global_load_dwordx4 v[240:243], v124, s[0:1] offset:256 nt
	s_add_u32 s0, s0, 0x5800
	s_addc_u32 s1, s1, 0
	global_load_dwordx4 v[194:197], v124, s[0:1] nt
	global_load_dwordx4 v[244:247], v124, s[0:1] offset:256 nt
	s_add_u32 s0, s0, 0x5800
	s_addc_u32 s1, s1, 0
	global_load_dwordx4 v[198:201], v124, s[0:1] nt
	global_load_dwordx4 v[248:251], v124, s[0:1] offset:256 nt
	s_add_u32 s0, s0, 0x5800
	s_addc_u32 s1, s1, 0
	global_load_dwordx4 v[130:133], v124, s[0:1] nt
	global_load_dwordx4 v[50:53], v124, s[0:1] offset:256 nt
	s_add_u32 s0, s0, 0x5800
	s_addc_u32 s1, s1, 0
	global_load_dwordx4 v[134:137], v124, s[0:1] nt
	global_load_dwordx4 v[54:57], v124, s[0:1] offset:256 nt
	s_add_u32 s0, s0, 0x5800
	s_addc_u32 s1, s1, 0
	global_load_dwordx4 v[138:141], v124, s[0:1] nt
	global_load_dwordx4 v[58:61], v124, s[0:1] offset:256 nt
	s_add_u32 s0, s0, 0x5800
	s_addc_u32 s1, s1, 0
	global_load_dwordx4 v[142:145], v124, s[0:1] nt
	global_load_dwordx4 v[62:65], v124, s[0:1] offset:256 nt
	s_mov_b64 exec, 1
	global_atomic_add v18, v16, v17, s[6:7] sc0
	s_mov_b64 exec, -1
	s_waitcnt vmcnt(1)
	v_mul_f32_e32 v98, v154, v82
	v_mul_f32_e32 v99, v155, v82
	v_mul_f32_e32 v100, v156, v82
	v_mul_f32_e32 v101, v157, v82
	v_mul_f32_e32 v154, v154, v66
	v_mul_f32_e32 v155, v155, v66
	v_mul_f32_e32 v156, v156, v66
	v_mul_f32_e32 v157, v157, v66
	v_fmac_f32_e32 v98, v158, v83
	v_fmac_f32_e32 v99, v159, v83
	v_fmac_f32_e32 v100, v160, v83
	v_fmac_f32_e32 v101, v161, v83
	v_mul_f32_e32 v158, v158, v67
	v_mul_f32_e32 v159, v159, v67
	v_mul_f32_e32 v160, v160, v67
	v_mul_f32_e32 v161, v161, v67
	v_fmac_f32_e32 v98, v162, v84
	v_fmac_f32_e32 v99, v163, v84
	v_fmac_f32_e32 v100, v164, v84
	v_fmac_f32_e32 v101, v165, v84
	v_mul_f32_e32 v162, v162, v68
	v_mul_f32_e32 v163, v163, v68
	v_mul_f32_e32 v164, v164, v68
	v_mul_f32_e32 v165, v165, v68
	v_fmac_f32_e32 v98, v166, v85
	v_fmac_f32_e32 v99, v167, v85
	v_fmac_f32_e32 v100, v168, v85
	v_fmac_f32_e32 v101, v169, v85
	v_mul_f32_e32 v166, v166, v69
	v_mul_f32_e32 v167, v167, v69
	v_mul_f32_e32 v168, v168, v69
	v_mul_f32_e32 v169, v169, v69
	v_fmac_f32_e32 v98, v170, v86
	v_fmac_f32_e32 v99, v171, v86
	v_fmac_f32_e32 v100, v172, v86
	v_fmac_f32_e32 v101, v173, v86
	v_mul_f32_e32 v170, v170, v70
	v_mul_f32_e32 v171, v171, v70
	v_mul_f32_e32 v172, v172, v70
	v_mul_f32_e32 v173, v173, v70
	v_fmac_f32_e32 v98, v174, v87
	v_fmac_f32_e32 v99, v175, v87
	v_fmac_f32_e32 v100, v176, v87
	v_fmac_f32_e32 v101, v177, v87
	v_mul_f32_e32 v174, v174, v71
	v_mul_f32_e32 v175, v175, v71
	v_mul_f32_e32 v176, v176, v71
	v_mul_f32_e32 v177, v177, v71
	v_fmac_f32_e32 v98, v178, v88
	v_fmac_f32_e32 v99, v179, v88
	v_fmac_f32_e32 v100, v180, v88
	v_fmac_f32_e32 v101, v181, v88
	v_mul_f32_e32 v178, v178, v72
	v_mul_f32_e32 v179, v179, v72
	v_mul_f32_e32 v180, v180, v72
	v_mul_f32_e32 v181, v181, v72
	v_fmac_f32_e32 v98, v182, v89
	v_fmac_f32_e32 v99, v183, v89
	v_fmac_f32_e32 v100, v184, v89
	v_fmac_f32_e32 v101, v185, v89
	v_mul_f32_e32 v182, v182, v73
	v_mul_f32_e32 v183, v183, v73
	v_mul_f32_e32 v184, v184, v73
	v_mul_f32_e32 v185, v185, v73
	v_fmac_f32_e32 v98, v186, v90
	v_fmac_f32_e32 v99, v187, v90
	v_fmac_f32_e32 v100, v188, v90
	v_fmac_f32_e32 v101, v189, v90
	v_mul_f32_e32 v186, v186, v74
	v_mul_f32_e32 v187, v187, v74
	v_mul_f32_e32 v188, v188, v74
	v_mul_f32_e32 v189, v189, v74
	v_fmac_f32_e32 v98, v190, v91
	v_fmac_f32_e32 v99, v191, v91
	v_fmac_f32_e32 v100, v192, v91
	v_fmac_f32_e32 v101, v193, v91
	v_mul_f32_e32 v190, v190, v75
	v_mul_f32_e32 v191, v191, v75
	v_mul_f32_e32 v192, v192, v75
	v_mul_f32_e32 v193, v193, v75
	v_fmac_f32_e32 v98, v194, v92
	v_fmac_f32_e32 v99, v195, v92
	v_fmac_f32_e32 v100, v196, v92
	v_fmac_f32_e32 v101, v197, v92
	v_mul_f32_e32 v194, v194, v76
	v_mul_f32_e32 v195, v195, v76
	v_mul_f32_e32 v196, v196, v76
	v_mul_f32_e32 v197, v197, v76
	v_fmac_f32_e32 v98, v198, v93
	v_fmac_f32_e32 v99, v199, v93
	v_fmac_f32_e32 v100, v200, v93
	v_fmac_f32_e32 v101, v201, v93
	v_mul_f32_e32 v198, v198, v77
	v_mul_f32_e32 v199, v199, v77
	v_mul_f32_e32 v200, v200, v77
	v_mul_f32_e32 v201, v201, v77
	v_fmac_f32_e32 v98, v130, v94
	v_fmac_f32_e32 v99, v131, v94
	v_fmac_f32_e32 v100, v132, v94
	v_fmac_f32_e32 v101, v133, v94
	v_mul_f32_e32 v130, v130, v78
	v_mul_f32_e32 v131, v131, v78
	v_mul_f32_e32 v132, v132, v78
	v_mul_f32_e32 v133, v133, v78
	v_fmac_f32_e32 v98, v134, v95
	v_fmac_f32_e32 v99, v135, v95
	v_fmac_f32_e32 v100, v136, v95
	v_fmac_f32_e32 v101, v137, v95
	v_mul_f32_e32 v134, v134, v79
	v_mul_f32_e32 v135, v135, v79
	v_mul_f32_e32 v136, v136, v79
	v_mul_f32_e32 v137, v137, v79
	v_fmac_f32_e32 v98, v138, v96
	v_fmac_f32_e32 v99, v139, v96
	v_fmac_f32_e32 v100, v140, v96
	v_fmac_f32_e32 v101, v141, v96
	v_mul_f32_e32 v138, v138, v80
	v_mul_f32_e32 v139, v139, v80
	v_mul_f32_e32 v140, v140, v80
	v_mul_f32_e32 v141, v141, v80
	v_fmac_f32_e32 v98, v142, v97
	v_fmac_f32_e32 v99, v143, v97
	v_fmac_f32_e32 v100, v144, v97
	v_fmac_f32_e32 v101, v145, v97
	v_mul_f32_e32 v142, v142, v81
	v_mul_f32_e32 v143, v143, v81
	v_mul_f32_e32 v144, v144, v81
	v_mul_f32_e32 v145, v145, v81
	v_lshlrev_b32_e32 v2, 2, v125
	v_lshlrev_b32_e32 v3, 12, v125
	v_lshl_add_u32 v3, v7, 1, v3
	ds_bpermute_b32 v106, v48, v98
	ds_bpermute_b32 v107, v48, v99
	ds_bpermute_b32 v108, v48, v100
	ds_bpermute_b32 v109, v48, v101
	s_waitcnt lgkmcnt(0)
	v_add_f32_e32 v98, v98, v106
	v_add_f32_e32 v99, v99, v107
	v_add_f32_e32 v100, v100, v108
	v_add_f32_e32 v101, v101, v109
	ds_bpermute_b32 v106, v1, v98
	ds_bpermute_b32 v107, v1, v99
	ds_bpermute_b32 v108, v1, v100
	ds_bpermute_b32 v109, v1, v101
	s_waitcnt lgkmcnt(0)
	v_add_f32_e32 v98, v98, v106
	v_add_f32_e32 v99, v99, v107
	v_add_f32_e32 v100, v100, v108
	v_add_f32_e32 v101, v101, v109
	s_mov_b64 exec, s[36:37]
	global_atomic_add_f32 v2, v98, s[74:75] offset:0
	global_atomic_add_f32 v2, v99, s[74:75] offset:4
	global_atomic_add_f32 v2, v100, s[74:75] offset:8
	global_atomic_add_f32 v2, v101, s[74:75] offset:12
	s_mov_b64 exec, -1
	v_cvt_pk_bf16_f32 v20, v154, v158
	v_cvt_pk_bf16_f32 v21, v162, v166
	v_cvt_pk_bf16_f32 v22, v170, v174
	v_cvt_pk_bf16_f32 v23, v178, v182
	global_store_dwordx4 v3, v[20:23], s[2:3]
	v_cvt_pk_bf16_f32 v24, v186, v190
	v_cvt_pk_bf16_f32 v25, v194, v198
	v_cvt_pk_bf16_f32 v26, v130, v134
	v_cvt_pk_bf16_f32 v27, v138, v142
	global_store_dwordx4 v3, v[24:27], s[2:3] offset:16
	v_lshlrev_b32_e32 v19, 16, v20
	v_and_b32_e32 v114, 0xffff0000, v20
	v_add_f32_e32 v114, v19, v114
	v_lshlrev_b32_e32 v19, 16, v21
	v_and_b32_e32 v115, 0xffff0000, v21
	v_add_f32_e32 v115, v19, v115
	v_lshlrev_b32_e32 v19, 16, v22
	v_and_b32_e32 v116, 0xffff0000, v22
	v_add_f32_e32 v116, v19, v116
	v_lshlrev_b32_e32 v19, 16, v23
	v_and_b32_e32 v117, 0xffff0000, v23
	v_add_f32_e32 v117, v19, v117
	v_lshlrev_b32_e32 v19, 16, v24
	v_and_b32_e32 v118, 0xffff0000, v24
	v_add_f32_e32 v118, v19, v118
	v_lshlrev_b32_e32 v19, 16, v25
	v_and_b32_e32 v119, 0xffff0000, v25
	v_add_f32_e32 v119, v19, v119
	v_lshlrev_b32_e32 v19, 16, v26
	v_and_b32_e32 v120, 0xffff0000, v26
	v_add_f32_e32 v120, v19, v120
	v_lshlrev_b32_e32 v19, 16, v27
	v_and_b32_e32 v121, 0xffff0000, v27
	v_add_f32_e32 v121, v19, v121
	v_add_f32_e32 v114, v114, v115
	v_add_f32_e32 v116, v116, v117
	v_add_f32_e32 v118, v118, v119
	v_add_f32_e32 v120, v120, v121
	v_add_f32_e32 v114, v114, v116
	v_add_f32_e32 v118, v118, v120
	v_add_f32_e32 v110, v114, v118
	s_add_u32 s2, s2, 0x1000
	s_addc_u32 s3, s3, 0
	v_cvt_pk_bf16_f32 v28, v155, v159
	v_cvt_pk_bf16_f32 v29, v163, v167
	v_cvt_pk_bf16_f32 v30, v171, v175
	v_cvt_pk_bf16_f32 v31, v179, v183
	global_store_dwordx4 v3, v[28:31], s[2:3]
	v_cvt_pk_bf16_f32 v32, v187, v191
	v_cvt_pk_bf16_f32 v33, v195, v199
	v_cvt_pk_bf16_f32 v34, v131, v135
	v_cvt_pk_bf16_f32 v35, v139, v143
	global_store_dwordx4 v3, v[32:35], s[2:3] offset:16
	v_lshlrev_b32_e32 v19, 16, v28
	v_and_b32_e32 v114, 0xffff0000, v28
	v_add_f32_e32 v114, v19, v114
	v_lshlrev_b32_e32 v19, 16, v29
	v_and_b32_e32 v115, 0xffff0000, v29
	v_add_f32_e32 v115, v19, v115
	v_lshlrev_b32_e32 v19, 16, v30
	v_and_b32_e32 v116, 0xffff0000, v30
	v_add_f32_e32 v116, v19, v116
	v_lshlrev_b32_e32 v19, 16, v31
	v_and_b32_e32 v117, 0xffff0000, v31
	v_add_f32_e32 v117, v19, v117
	v_lshlrev_b32_e32 v19, 16, v32
	v_and_b32_e32 v118, 0xffff0000, v32
	v_add_f32_e32 v118, v19, v118
	v_lshlrev_b32_e32 v19, 16, v33
	v_and_b32_e32 v119, 0xffff0000, v33
	v_add_f32_e32 v119, v19, v119
	v_lshlrev_b32_e32 v19, 16, v34
	v_and_b32_e32 v120, 0xffff0000, v34
	v_add_f32_e32 v120, v19, v120
	v_lshlrev_b32_e32 v19, 16, v35
	v_and_b32_e32 v121, 0xffff0000, v35
	v_add_f32_e32 v121, v19, v121
	v_add_f32_e32 v114, v114, v115
	v_add_f32_e32 v116, v116, v117
	v_add_f32_e32 v118, v118, v119
	v_add_f32_e32 v120, v120, v121
	v_add_f32_e32 v114, v114, v116
	v_add_f32_e32 v118, v118, v120
	v_add_f32_e32 v111, v114, v118
	s_add_u32 s2, s2, 0x1000
	s_addc_u32 s3, s3, 0
	v_cvt_pk_bf16_f32 v36, v156, v160
	v_cvt_pk_bf16_f32 v37, v164, v168
	v_cvt_pk_bf16_f32 v38, v172, v176
	v_cvt_pk_bf16_f32 v39, v180, v184
	global_store_dwordx4 v3, v[36:39], s[2:3]
	v_cvt_pk_bf16_f32 v40, v188, v192
	v_cvt_pk_bf16_f32 v41, v196, v200
	v_cvt_pk_bf16_f32 v42, v132, v136
	v_cvt_pk_bf16_f32 v43, v140, v144
	global_store_dwordx4 v3, v[40:43], s[2:3] offset:16
	v_lshlrev_b32_e32 v19, 16, v36
	v_and_b32_e32 v114, 0xffff0000, v36
	v_add_f32_e32 v114, v19, v114
	v_lshlrev_b32_e32 v19, 16, v37
	v_and_b32_e32 v115, 0xffff0000, v37
	v_add_f32_e32 v115, v19, v115
	v_lshlrev_b32_e32 v19, 16, v38
	v_and_b32_e32 v116, 0xffff0000, v38
	v_add_f32_e32 v116, v19, v116
	v_lshlrev_b32_e32 v19, 16, v39
	v_and_b32_e32 v117, 0xffff0000, v39
	v_add_f32_e32 v117, v19, v117
	v_lshlrev_b32_e32 v19, 16, v40
	v_and_b32_e32 v118, 0xffff0000, v40
	v_add_f32_e32 v118, v19, v118
	v_lshlrev_b32_e32 v19, 16, v41
	v_and_b32_e32 v119, 0xffff0000, v41
	v_add_f32_e32 v119, v19, v119
	v_lshlrev_b32_e32 v19, 16, v42
	v_and_b32_e32 v120, 0xffff0000, v42
	v_add_f32_e32 v120, v19, v120
	v_lshlrev_b32_e32 v19, 16, v43
	v_and_b32_e32 v121, 0xffff0000, v43
	v_add_f32_e32 v121, v19, v121
	v_add_f32_e32 v114, v114, v115
	v_add_f32_e32 v116, v116, v117
	v_add_f32_e32 v118, v118, v119
	v_add_f32_e32 v120, v120, v121
	v_add_f32_e32 v114, v114, v116
	v_add_f32_e32 v118, v118, v120
	v_add_f32_e32 v112, v114, v118
	s_add_u32 s2, s2, 0x1000
	s_addc_u32 s3, s3, 0
	v_cvt_pk_bf16_f32 v20, v157, v161
	v_cvt_pk_bf16_f32 v21, v165, v169
	v_cvt_pk_bf16_f32 v22, v173, v177
	v_cvt_pk_bf16_f32 v23, v181, v185
	global_store_dwordx4 v3, v[20:23], s[2:3]
	v_cvt_pk_bf16_f32 v24, v189, v193
	v_cvt_pk_bf16_f32 v25, v197, v201
	v_cvt_pk_bf16_f32 v26, v133, v137
	v_cvt_pk_bf16_f32 v27, v141, v145
	global_store_dwordx4 v3, v[24:27], s[2:3] offset:16
	v_lshlrev_b32_e32 v19, 16, v20
	v_and_b32_e32 v114, 0xffff0000, v20
	v_add_f32_e32 v114, v19, v114
	v_lshlrev_b32_e32 v19, 16, v21
	v_and_b32_e32 v115, 0xffff0000, v21
	v_add_f32_e32 v115, v19, v115
	v_lshlrev_b32_e32 v19, 16, v22
	v_and_b32_e32 v116, 0xffff0000, v22
	v_add_f32_e32 v116, v19, v116
	v_lshlrev_b32_e32 v19, 16, v23
	v_and_b32_e32 v117, 0xffff0000, v23
	v_add_f32_e32 v117, v19, v117
	v_lshlrev_b32_e32 v19, 16, v24
	v_and_b32_e32 v118, 0xffff0000, v24
	v_add_f32_e32 v118, v19, v118
	v_lshlrev_b32_e32 v19, 16, v25
	v_and_b32_e32 v119, 0xffff0000, v25
	v_add_f32_e32 v119, v19, v119
	v_lshlrev_b32_e32 v19, 16, v26
	v_and_b32_e32 v120, 0xffff0000, v26
	v_add_f32_e32 v120, v19, v120
	v_lshlrev_b32_e32 v19, 16, v27
	v_and_b32_e32 v121, 0xffff0000, v27
	v_add_f32_e32 v121, v19, v121
	v_add_f32_e32 v114, v114, v115
	v_add_f32_e32 v116, v116, v117
	v_add_f32_e32 v118, v118, v119
	v_add_f32_e32 v120, v120, v121
	v_add_f32_e32 v114, v114, v116
	v_add_f32_e32 v118, v118, v120
	v_add_f32_e32 v113, v114, v118
	ds_bpermute_b32 v106, v48, v110
	ds_bpermute_b32 v107, v48, v111
	ds_bpermute_b32 v108, v48, v112
	ds_bpermute_b32 v109, v48, v113
	s_waitcnt lgkmcnt(0)
	v_add_f32_e32 v110, v110, v106
	v_add_f32_e32 v111, v111, v107
	v_add_f32_e32 v112, v112, v108
	v_add_f32_e32 v113, v113, v109
	ds_bpermute_b32 v106, v1, v110
	ds_bpermute_b32 v107, v1, v111
	ds_bpermute_b32 v108, v1, v112
	ds_bpermute_b32 v109, v1, v113
	s_waitcnt lgkmcnt(0)
	v_add_f32_e32 v110, v110, v106
	v_add_f32_e32 v111, v111, v107
	v_add_f32_e32 v112, v112, v108
	v_add_f32_e32 v113, v113, v109
	s_mov_b64 exec, s[36:37]
	global_atomic_add_f32 v2, v110, s[72:73] offset:0
	global_atomic_add_f32 v2, v111, s[72:73] offset:4
	global_atomic_add_f32 v2, v112, s[72:73] offset:8
	global_atomic_add_f32 v2, v113, s[72:73] offset:12
	s_mov_b64 exec, -1
	v_mul_f32_e32 v98, v204, v82
	v_mul_f32_e32 v99, v205, v82
	v_mul_f32_e32 v100, v206, v82
	v_mul_f32_e32 v101, v207, v82
	v_mul_f32_e32 v204, v204, v66
	v_mul_f32_e32 v205, v205, v66
	v_mul_f32_e32 v206, v206, v66
	v_mul_f32_e32 v207, v207, v66
	v_fmac_f32_e32 v98, v208, v83
	v_fmac_f32_e32 v99, v209, v83
	v_fmac_f32_e32 v100, v210, v83
	v_fmac_f32_e32 v101, v211, v83
	v_mul_f32_e32 v208, v208, v67
	v_mul_f32_e32 v209, v209, v67
	v_mul_f32_e32 v210, v210, v67
	v_mul_f32_e32 v211, v211, v67
	v_fmac_f32_e32 v98, v212, v84
	v_fmac_f32_e32 v99, v213, v84
	v_fmac_f32_e32 v100, v214, v84
	v_fmac_f32_e32 v101, v215, v84
	v_mul_f32_e32 v212, v212, v68
	v_mul_f32_e32 v213, v213, v68
	v_mul_f32_e32 v214, v214, v68
	v_mul_f32_e32 v215, v215, v68
	v_fmac_f32_e32 v98, v216, v85
	v_fmac_f32_e32 v99, v217, v85
	v_fmac_f32_e32 v100, v218, v85
	v_fmac_f32_e32 v101, v219, v85
	v_mul_f32_e32 v216, v216, v69
	v_mul_f32_e32 v217, v217, v69
	v_mul_f32_e32 v218, v218, v69
	v_mul_f32_e32 v219, v219, v69
	v_fmac_f32_e32 v98, v220, v86
	v_fmac_f32_e32 v99, v221, v86
	v_fmac_f32_e32 v100, v222, v86
	v_fmac_f32_e32 v101, v223, v86
	v_mul_f32_e32 v220, v220, v70
	v_mul_f32_e32 v221, v221, v70
	v_mul_f32_e32 v222, v222, v70
	v_mul_f32_e32 v223, v223, v70
	v_fmac_f32_e32 v98, v224, v87
	v_fmac_f32_e32 v99, v225, v87
	v_fmac_f32_e32 v100, v226, v87
	v_fmac_f32_e32 v101, v227, v87
	v_mul_f32_e32 v224, v224, v71
	v_mul_f32_e32 v225, v225, v71
	v_mul_f32_e32 v226, v226, v71
	v_mul_f32_e32 v227, v227, v71
	v_fmac_f32_e32 v98, v228, v88
	v_fmac_f32_e32 v99, v229, v88
	v_fmac_f32_e32 v100, v230, v88
	v_fmac_f32_e32 v101, v231, v88
	v_mul_f32_e32 v228, v228, v72
	v_mul_f32_e32 v229, v229, v72
	v_mul_f32_e32 v230, v230, v72
	v_mul_f32_e32 v231, v231, v72
	v_fmac_f32_e32 v98, v232, v89
	v_fmac_f32_e32 v99, v233, v89
	v_fmac_f32_e32 v100, v234, v89
	v_fmac_f32_e32 v101, v235, v89
	v_mul_f32_e32 v232, v232, v73
	v_mul_f32_e32 v233, v233, v73
	v_mul_f32_e32 v234, v234, v73
	v_mul_f32_e32 v235, v235, v73
	v_fmac_f32_e32 v98, v236, v90
	v_fmac_f32_e32 v99, v237, v90
	v_fmac_f32_e32 v100, v238, v90
	v_fmac_f32_e32 v101, v239, v90
	v_mul_f32_e32 v236, v236, v74
	v_mul_f32_e32 v237, v237, v74
	v_mul_f32_e32 v238, v238, v74
	v_mul_f32_e32 v239, v239, v74
	v_fmac_f32_e32 v98, v240, v91
	v_fmac_f32_e32 v99, v241, v91
	v_fmac_f32_e32 v100, v242, v91
	v_fmac_f32_e32 v101, v243, v91
	v_mul_f32_e32 v240, v240, v75
	v_mul_f32_e32 v241, v241, v75
	v_mul_f32_e32 v242, v242, v75
	v_mul_f32_e32 v243, v243, v75
	v_fmac_f32_e32 v98, v244, v92
	v_fmac_f32_e32 v99, v245, v92
	v_fmac_f32_e32 v100, v246, v92
	v_fmac_f32_e32 v101, v247, v92
	v_mul_f32_e32 v244, v244, v76
	v_mul_f32_e32 v245, v245, v76
	v_mul_f32_e32 v246, v246, v76
	v_mul_f32_e32 v247, v247, v76
	v_fmac_f32_e32 v98, v248, v93
	v_fmac_f32_e32 v99, v249, v93
	v_fmac_f32_e32 v100, v250, v93
	v_fmac_f32_e32 v101, v251, v93
	v_mul_f32_e32 v248, v248, v77
	v_mul_f32_e32 v249, v249, v77
	v_mul_f32_e32 v250, v250, v77
	v_mul_f32_e32 v251, v251, v77
	v_fmac_f32_e32 v98, v50, v94
	v_fmac_f32_e32 v99, v51, v94
	v_fmac_f32_e32 v100, v52, v94
	v_fmac_f32_e32 v101, v53, v94
	v_mul_f32_e32 v50, v50, v78
	v_mul_f32_e32 v51, v51, v78
	v_mul_f32_e32 v52, v52, v78
	v_mul_f32_e32 v53, v53, v78
	v_fmac_f32_e32 v98, v54, v95
	v_fmac_f32_e32 v99, v55, v95
	v_fmac_f32_e32 v100, v56, v95
	v_fmac_f32_e32 v101, v57, v95
	v_mul_f32_e32 v54, v54, v79
	v_mul_f32_e32 v55, v55, v79
	v_mul_f32_e32 v56, v56, v79
	v_mul_f32_e32 v57, v57, v79
	v_fmac_f32_e32 v98, v58, v96
	v_fmac_f32_e32 v99, v59, v96
	v_fmac_f32_e32 v100, v60, v96
	v_fmac_f32_e32 v101, v61, v96
	v_mul_f32_e32 v58, v58, v80
	v_mul_f32_e32 v59, v59, v80
	v_mul_f32_e32 v60, v60, v80
	v_mul_f32_e32 v61, v61, v80
	v_fmac_f32_e32 v98, v62, v97
	v_fmac_f32_e32 v99, v63, v97
	v_fmac_f32_e32 v100, v64, v97
	v_fmac_f32_e32 v101, v65, v97
	v_mul_f32_e32 v62, v62, v81
	v_mul_f32_e32 v63, v63, v81
	v_mul_f32_e32 v64, v64, v81
	v_mul_f32_e32 v65, v65, v81
	v_lshlrev_b32_e32 v2, 2, v125
	v_lshlrev_b32_e32 v3, 12, v125
	v_lshl_add_u32 v3, v7, 1, v3
	ds_bpermute_b32 v106, v48, v98
	ds_bpermute_b32 v107, v48, v99
	ds_bpermute_b32 v108, v48, v100
	ds_bpermute_b32 v109, v48, v101
	s_waitcnt lgkmcnt(0)
	v_add_f32_e32 v98, v98, v106
	v_add_f32_e32 v99, v99, v107
	v_add_f32_e32 v100, v100, v108
	v_add_f32_e32 v101, v101, v109
	ds_bpermute_b32 v106, v1, v98
	ds_bpermute_b32 v107, v1, v99
	ds_bpermute_b32 v108, v1, v100
	ds_bpermute_b32 v109, v1, v101
	s_waitcnt lgkmcnt(0)
	v_add_f32_e32 v98, v98, v106
	v_add_f32_e32 v99, v99, v107
	v_add_f32_e32 v100, v100, v108
	v_add_f32_e32 v101, v101, v109
	s_mov_b64 exec, s[36:37]
	global_atomic_add_f32 v2, v98, s[78:79] offset:0
	global_atomic_add_f32 v2, v99, s[78:79] offset:4
	global_atomic_add_f32 v2, v100, s[78:79] offset:8
	global_atomic_add_f32 v2, v101, s[78:79] offset:12
	s_mov_b64 exec, -1
	v_cvt_pk_bf16_f32 v20, v204, v208
	v_cvt_pk_bf16_f32 v21, v212, v216
	v_cvt_pk_bf16_f32 v22, v220, v224
	v_cvt_pk_bf16_f32 v23, v228, v232
	global_store_dwordx4 v3, v[20:23], s[4:5]
	v_cvt_pk_bf16_f32 v24, v236, v240
	v_cvt_pk_bf16_f32 v25, v244, v248
	v_cvt_pk_bf16_f32 v26, v50, v54
	v_cvt_pk_bf16_f32 v27, v58, v62
	global_store_dwordx4 v3, v[24:27], s[4:5] offset:16
	v_lshlrev_b32_e32 v19, 16, v20
	v_and_b32_e32 v114, 0xffff0000, v20
	v_add_f32_e32 v114, v19, v114
	v_lshlrev_b32_e32 v19, 16, v21
	v_and_b32_e32 v115, 0xffff0000, v21
	v_add_f32_e32 v115, v19, v115
	v_lshlrev_b32_e32 v19, 16, v22
	v_and_b32_e32 v116, 0xffff0000, v22
	v_add_f32_e32 v116, v19, v116
	v_lshlrev_b32_e32 v19, 16, v23
	v_and_b32_e32 v117, 0xffff0000, v23
	v_add_f32_e32 v117, v19, v117
	v_lshlrev_b32_e32 v19, 16, v24
	v_and_b32_e32 v118, 0xffff0000, v24
	v_add_f32_e32 v118, v19, v118
	v_lshlrev_b32_e32 v19, 16, v25
	v_and_b32_e32 v119, 0xffff0000, v25
	v_add_f32_e32 v119, v19, v119
	v_lshlrev_b32_e32 v19, 16, v26
	v_and_b32_e32 v120, 0xffff0000, v26
	v_add_f32_e32 v120, v19, v120
	v_lshlrev_b32_e32 v19, 16, v27
	v_and_b32_e32 v121, 0xffff0000, v27
	v_add_f32_e32 v121, v19, v121
	v_add_f32_e32 v114, v114, v115
	v_add_f32_e32 v116, v116, v117
	v_add_f32_e32 v118, v118, v119
	v_add_f32_e32 v120, v120, v121
	v_add_f32_e32 v114, v114, v116
	v_add_f32_e32 v118, v118, v120
	v_add_f32_e32 v110, v114, v118
	s_add_u32 s4, s4, 0x1000
	s_addc_u32 s5, s5, 0
	v_cvt_pk_bf16_f32 v28, v205, v209
	v_cvt_pk_bf16_f32 v29, v213, v217
	v_cvt_pk_bf16_f32 v30, v221, v225
	v_cvt_pk_bf16_f32 v31, v229, v233
	global_store_dwordx4 v3, v[28:31], s[4:5]
	v_cvt_pk_bf16_f32 v32, v237, v241
	v_cvt_pk_bf16_f32 v33, v245, v249
	v_cvt_pk_bf16_f32 v34, v51, v55
	v_cvt_pk_bf16_f32 v35, v59, v63
	global_store_dwordx4 v3, v[32:35], s[4:5] offset:16
	v_lshlrev_b32_e32 v19, 16, v28
	v_and_b32_e32 v114, 0xffff0000, v28
	v_add_f32_e32 v114, v19, v114
	v_lshlrev_b32_e32 v19, 16, v29
	v_and_b32_e32 v115, 0xffff0000, v29
	v_add_f32_e32 v115, v19, v115
	v_lshlrev_b32_e32 v19, 16, v30
	v_and_b32_e32 v116, 0xffff0000, v30
	v_add_f32_e32 v116, v19, v116
	v_lshlrev_b32_e32 v19, 16, v31
	v_and_b32_e32 v117, 0xffff0000, v31
	v_add_f32_e32 v117, v19, v117
	v_lshlrev_b32_e32 v19, 16, v32
	v_and_b32_e32 v118, 0xffff0000, v32
	v_add_f32_e32 v118, v19, v118
	v_lshlrev_b32_e32 v19, 16, v33
	v_and_b32_e32 v119, 0xffff0000, v33
	v_add_f32_e32 v119, v19, v119
	v_lshlrev_b32_e32 v19, 16, v34
	v_and_b32_e32 v120, 0xffff0000, v34
	v_add_f32_e32 v120, v19, v120
	v_lshlrev_b32_e32 v19, 16, v35
	v_and_b32_e32 v121, 0xffff0000, v35
	v_add_f32_e32 v121, v19, v121
	v_add_f32_e32 v114, v114, v115
	v_add_f32_e32 v116, v116, v117
	v_add_f32_e32 v118, v118, v119
	v_add_f32_e32 v120, v120, v121
	v_add_f32_e32 v114, v114, v116
	v_add_f32_e32 v118, v118, v120
	v_add_f32_e32 v111, v114, v118
	s_add_u32 s4, s4, 0x1000
	s_addc_u32 s5, s5, 0
	v_cvt_pk_bf16_f32 v36, v206, v210
	v_cvt_pk_bf16_f32 v37, v214, v218
	v_cvt_pk_bf16_f32 v38, v222, v226
	v_cvt_pk_bf16_f32 v39, v230, v234
	global_store_dwordx4 v3, v[36:39], s[4:5]
	v_cvt_pk_bf16_f32 v40, v238, v242
	v_cvt_pk_bf16_f32 v41, v246, v250
	v_cvt_pk_bf16_f32 v42, v52, v56
	v_cvt_pk_bf16_f32 v43, v60, v64
	global_store_dwordx4 v3, v[40:43], s[4:5] offset:16
	v_lshlrev_b32_e32 v19, 16, v36
	v_and_b32_e32 v114, 0xffff0000, v36
	v_add_f32_e32 v114, v19, v114
	v_lshlrev_b32_e32 v19, 16, v37
	v_and_b32_e32 v115, 0xffff0000, v37
	v_add_f32_e32 v115, v19, v115
	v_lshlrev_b32_e32 v19, 16, v38
	v_and_b32_e32 v116, 0xffff0000, v38
	v_add_f32_e32 v116, v19, v116
	v_lshlrev_b32_e32 v19, 16, v39
	v_and_b32_e32 v117, 0xffff0000, v39
	v_add_f32_e32 v117, v19, v117
	v_lshlrev_b32_e32 v19, 16, v40
	v_and_b32_e32 v118, 0xffff0000, v40
	v_add_f32_e32 v118, v19, v118
	v_lshlrev_b32_e32 v19, 16, v41
	v_and_b32_e32 v119, 0xffff0000, v41
	v_add_f32_e32 v119, v19, v119
	v_lshlrev_b32_e32 v19, 16, v42
	v_and_b32_e32 v120, 0xffff0000, v42
	v_add_f32_e32 v120, v19, v120
	v_lshlrev_b32_e32 v19, 16, v43
	v_and_b32_e32 v121, 0xffff0000, v43
	v_add_f32_e32 v121, v19, v121
	v_add_f32_e32 v114, v114, v115
	v_add_f32_e32 v116, v116, v117
	v_add_f32_e32 v118, v118, v119
	v_add_f32_e32 v120, v120, v121
	v_add_f32_e32 v114, v114, v116
	v_add_f32_e32 v118, v118, v120
	v_add_f32_e32 v112, v114, v118
	s_add_u32 s4, s4, 0x1000
	s_addc_u32 s5, s5, 0
	v_cvt_pk_bf16_f32 v20, v207, v211
	v_cvt_pk_bf16_f32 v21, v215, v219
	v_cvt_pk_bf16_f32 v22, v223, v227
	v_cvt_pk_bf16_f32 v23, v231, v235
	global_store_dwordx4 v3, v[20:23], s[4:5]
	v_cvt_pk_bf16_f32 v24, v239, v243
	v_cvt_pk_bf16_f32 v25, v247, v251
	v_cvt_pk_bf16_f32 v26, v53, v57
	v_cvt_pk_bf16_f32 v27, v61, v65
	global_store_dwordx4 v3, v[24:27], s[4:5] offset:16
	v_lshlrev_b32_e32 v19, 16, v20
	v_and_b32_e32 v114, 0xffff0000, v20
	v_add_f32_e32 v114, v19, v114
	v_lshlrev_b32_e32 v19, 16, v21
	v_and_b32_e32 v115, 0xffff0000, v21
	v_add_f32_e32 v115, v19, v115
	v_lshlrev_b32_e32 v19, 16, v22
	v_and_b32_e32 v116, 0xffff0000, v22
	v_add_f32_e32 v116, v19, v116
	v_lshlrev_b32_e32 v19, 16, v23
	v_and_b32_e32 v117, 0xffff0000, v23
	v_add_f32_e32 v117, v19, v117
	v_lshlrev_b32_e32 v19, 16, v24
	v_and_b32_e32 v118, 0xffff0000, v24
	v_add_f32_e32 v118, v19, v118
	v_lshlrev_b32_e32 v19, 16, v25
	v_and_b32_e32 v119, 0xffff0000, v25
	v_add_f32_e32 v119, v19, v119
	v_lshlrev_b32_e32 v19, 16, v26
	v_and_b32_e32 v120, 0xffff0000, v26
	v_add_f32_e32 v120, v19, v120
	v_lshlrev_b32_e32 v19, 16, v27
	v_and_b32_e32 v121, 0xffff0000, v27
	v_add_f32_e32 v121, v19, v121
	v_add_f32_e32 v114, v114, v115
	v_add_f32_e32 v116, v116, v117
	v_add_f32_e32 v118, v118, v119
	v_add_f32_e32 v120, v120, v121
	v_add_f32_e32 v114, v114, v116
	v_add_f32_e32 v118, v118, v120
	v_add_f32_e32 v113, v114, v118
	ds_bpermute_b32 v106, v48, v110
	ds_bpermute_b32 v107, v48, v111
	ds_bpermute_b32 v108, v48, v112
	ds_bpermute_b32 v109, v48, v113
	s_waitcnt lgkmcnt(0)
	v_add_f32_e32 v110, v110, v106
	v_add_f32_e32 v111, v111, v107
	v_add_f32_e32 v112, v112, v108
	v_add_f32_e32 v113, v113, v109
	ds_bpermute_b32 v106, v1, v110
	ds_bpermute_b32 v107, v1, v111
	ds_bpermute_b32 v108, v1, v112
	ds_bpermute_b32 v109, v1, v113
	s_waitcnt lgkmcnt(0)
	v_add_f32_e32 v110, v110, v106
	v_add_f32_e32 v111, v111, v107
	v_add_f32_e32 v112, v112, v108
	v_add_f32_e32 v113, v113, v109
	s_mov_b64 exec, s[36:37]
	global_atomic_add_f32 v2, v110, s[76:77] offset:0
	global_atomic_add_f32 v2, v111, s[76:77] offset:4
	global_atomic_add_f32 v2, v112, s[76:77] offset:8
	global_atomic_add_f32 v2, v113, s[76:77] offset:12
	s_mov_b64 exec, -1
	s_waitcnt vmcnt(16)
	s_branch .Lw1d_loop

.LBB0_1229:
	s_or_b64 exec, exec, s[0:1]
	s_waitcnt lgkmcnt(0)
	s_barrier
	ds_read_b32 v1, v155
	s_movk_i32 s0, 0x677
	s_waitcnt lgkmcnt(0)
	v_add_u32_e32 v1, s98, v1
	v_cmp_lt_u32_e32 vcc, s0, v1
	v_readfirstlane_b32 s42, v1
	s_mov_b64 s[0:1], -1
	s_cbranch_vccnz .LBB0_1224
	s_cmpk_gt_u32 s42, 0x2ff
	s_cbranch_scc1 .Lq_nomap
	s_cmpk_lt_u32 s42, 0xc0
	s_cbranch_scc1 .Lq_nomap
	s_cmpk_lt_u32 s42, 0x2c0
	s_cbranch_scc1 .Lq_g1
	s_sub_u32 s42, s42, 0x200
	s_branch .Lq_nomap
